# f32 V-cache outputs no longer written in HBM-bound phase 2; idle blocks at the ends of P4/P5 write them from P (exact bf16->f32 images)
# baseline (speedup 1.0000x reference)
.LBB0_379:
	s_andn2_saveexec_b64 s[8:9], s[10:11]
	v_mov_b32_e32 v44, v59
	v_pk_mul_f32 v[44:45], v[46:47], v[44:45]
	s_nop 0
	v_sub_f32_e32 v59, v44, v45
	s_or_b64 exec, exec, s[8:9]
	v_cvt_pk_bf16_f32 v44, v68, v69
	v_cvt_pk_bf16_f32 v45, v70, v71
	v_cvt_pk_bf16_f32 v46, v56, v57
	v_cvt_pk_bf16_f32 v47, v58, v59
	global_store_dwordx4 v[122:123], v[68:71], off offset:2048
	global_store_dwordx4 v[122:123], v[56:59], off offset:2064
	global_store_dwordx4 v[72:73], v[44:47], off offset:1024
	v_lshl_add_u64 v[48:49], s[34:35], 0, v[84:85]
	v_lshlrev_b32_e32 v50, 16, v40
	v_lshl_add_u64 v[46:47], s[26:27], 0, v[82:83]
	v_cndmask_b32_e32 v59, v47, v49, vcc
	v_cndmask_b32_e32 v58, v46, v48, vcc
	v_lshl_add_u64 v[44:45], s[40:41], 0, v[86:87]
	v_and_b32_e32 v51, 0xffff0000, v40
	v_lshlrev_b32_e32 v52, 16, v41
	v_and_b32_e32 v53, 0xffff0000, v41
	v_lshl_add_u64 v[58:59], v[58:59], 0, v[90:91]
	v_lshlrev_b32_e32 v54, 16, v42
	v_and_b32_e32 v55, 0xffff0000, v42
	v_lshlrev_b32_e32 v56, 16, v43
	v_and_b32_e32 v57, 0xffff0000, v43
	s_nop 0
	s_nop 0
	s_and_saveexec_b64 s[8:9], vcc
	s_cbranch_execz .LBB0_383
	v_mov_b32_e32 v121, v91
	v_lshl_add_u64 v[46:47], v[44:45], 0, v[120:121]
	global_store_dwordx4 v[46:47], v[40:43], off
	v_mov_b64_e32 v[46:47], v[48:49]
.LBB0_383:
	s_or_b64 exec, exec, s[8:9]
	v_lshlrev_b32_e32 v40, 16, v36
	v_and_b32_e32 v41, 0xffff0000, v36
	v_lshlrev_b32_e32 v42, 16, v37
	v_and_b32_e32 v43, 0xffff0000, v37
	v_lshl_add_u64 v[46:47], v[46:47], 0, v[90:91]
	v_lshlrev_b32_e32 v48, 16, v38
	v_and_b32_e32 v49, 0xffff0000, v38
	v_lshlrev_b32_e32 v50, 16, v39
	v_and_b32_e32 v51, 0xffff0000, v39
	s_nop 0
	s_nop 0
	s_and_saveexec_b64 s[8:9], vcc
	s_cbranch_execz .LBB0_385
	v_mov_b32_e32 v121, v91
	v_lshl_add_u64 v[40:41], v[44:45], 0, v[120:121]
	global_store_dwordx4 v[40:41], v[36:39], off offset:1024

.Ltb_done:
	s_cmp_lt_u32 s2, 0x80
	s_cbranch_scc1 .Lvoa_done
	v_lshrrev_b32_e32 v0, 6, v204
	v_and_b32_e32 v1, 63, v204
	v_lshlrev_b32_e32 v2, 4, v1
	v_lshlrev_b32_e32 v3, 5, v1
	v_readfirstlane_b32 s4, v0
	s_sub_u32 s5, s2, 0x80
	s_lshl_b32 s5, s5, 2
	s_add_u32 s4, s4, s5
	s_add_u32 s4, s4, 0x0
	s_cmpk_ge_u32 s4, 0x1100
	s_cbranch_scc1 .Lvoa_done
	s_mul_i32 s6, s4, 0x5400
	s_add_u32 s6, s6, 0x8009000
	s_add_u32 s10, s94, s6
	s_addc_u32 s11, s95, 0
	s_lshl_b32 s6, s4, 12
	s_add_u32 s7, s6, 0x6a00000
	s_add_u32 s6, s6, 0x6400000
	s_cmpk_lt_u32 s4, 0x2000
	s_cselect_b32 s6, s6, s7
	s_add_u32 s14, s92, s6
	s_addc_u32 s15, s93, 0
	global_load_dwordx4 v[8:11], v2, s[10:11]
	global_load_dwordx4 v[12:15], v2, s[10:11] offset:1024
.Lvoa_loop:
	s_add_u32 s12, s4, 1536
	s_cmpk_lt_u32 s12, 0x1100
	s_cselect_b32 s13, s12, s4
	s_mul_i32 s6, s13, 0x5400
	s_add_u32 s6, s6, 0x8009000
	s_add_u32 s10, s94, s6
	s_addc_u32 s11, s95, 0
	s_lshl_b32 s6, s13, 12
	s_add_u32 s7, s6, 0x6a00000
	s_add_u32 s6, s6, 0x6400000
	s_cmpk_lt_u32 s13, 0x2000
	s_cselect_b32 s6, s6, s7
	s_add_u32 s16, s92, s6
	s_addc_u32 s17, s93, 0
	global_load_dwordx4 v[16:19], v2, s[10:11]
	global_load_dwordx4 v[20:23], v2, s[10:11] offset:1024
	s_waitcnt vmcnt(2)
	v_lshlrev_b32_e32 v24, 16, v8
	v_and_b32_e32 v25, 0xffff0000, v8
	v_lshlrev_b32_e32 v26, 16, v9
	v_and_b32_e32 v27, 0xffff0000, v9
	v_lshlrev_b32_e32 v28, 16, v10
	v_and_b32_e32 v29, 0xffff0000, v10
	v_lshlrev_b32_e32 v30, 16, v11
	v_and_b32_e32 v31, 0xffff0000, v11
	v_lshlrev_b32_e32 v32, 16, v12
	v_and_b32_e32 v33, 0xffff0000, v12
	v_lshlrev_b32_e32 v34, 16, v13
	v_and_b32_e32 v35, 0xffff0000, v13
	v_lshlrev_b32_e32 v36, 16, v14
	v_and_b32_e32 v37, 0xffff0000, v14
	v_lshlrev_b32_e32 v38, 16, v15
	v_and_b32_e32 v39, 0xffff0000, v15
	global_store_dwordx4 v3, v[24:27], s[14:15]
	global_store_dwordx4 v3, v[28:31], s[14:15] offset:16
	global_store_dwordx4 v3, v[32:35], s[14:15] offset:2048
	global_store_dwordx4 v3, v[36:39], s[14:15] offset:2064
	s_mov_b32 s4, s12
	s_cmpk_lt_u32 s4, 0x1100
	s_cbranch_scc0 .Lvoa_drain
	s_add_u32 s12, s4, 1536
	s_cmpk_lt_u32 s12, 0x1100
	s_cselect_b32 s13, s12, s4
	s_mul_i32 s6, s13, 0x5400
	s_add_u32 s6, s6, 0x8009000
	s_add_u32 s10, s94, s6
	s_addc_u32 s11, s95, 0
	s_lshl_b32 s6, s13, 12
	s_add_u32 s7, s6, 0x6a00000
	s_add_u32 s6, s6, 0x6400000
	s_cmpk_lt_u32 s13, 0x2000
	s_cselect_b32 s6, s6, s7
	s_add_u32 s14, s92, s6
	s_addc_u32 s15, s93, 0
	global_load_dwordx4 v[8:11], v2, s[10:11]
	global_load_dwordx4 v[12:15], v2, s[10:11] offset:1024
	s_waitcnt vmcnt(2)
	v_lshlrev_b32_e32 v40, 16, v16
	v_and_b32_e32 v41, 0xffff0000, v16
	v_lshlrev_b32_e32 v42, 16, v17
	v_and_b32_e32 v43, 0xffff0000, v17
	v_lshlrev_b32_e32 v44, 16, v18
	v_and_b32_e32 v45, 0xffff0000, v18
	v_lshlrev_b32_e32 v46, 16, v19
	v_and_b32_e32 v47, 0xffff0000, v19
	v_lshlrev_b32_e32 v48, 16, v20
	v_and_b32_e32 v49, 0xffff0000, v20
	v_lshlrev_b32_e32 v50, 16, v21
	v_and_b32_e32 v51, 0xffff0000, v21
	v_lshlrev_b32_e32 v52, 16, v22
	v_and_b32_e32 v53, 0xffff0000, v22
	v_lshlrev_b32_e32 v54, 16, v23
	v_and_b32_e32 v55, 0xffff0000, v23
	global_store_dwordx4 v3, v[40:43], s[16:17]
	global_store_dwordx4 v3, v[44:47], s[16:17] offset:16
	global_store_dwordx4 v3, v[48:51], s[16:17] offset:2048
	global_store_dwordx4 v3, v[52:55], s[16:17] offset:2064
	s_mov_b32 s4, s12
	s_cmpk_lt_u32 s4, 0x1100
	s_cbranch_scc0 .Lvoa_drain
	s_branch .Lvoa_loop

.Lvoa_done:
	s_load_dword s3, s[0:1], 0x120
	s_add_u32 s4, s0, 0x120
	s_addc_u32 s5, s1, 0
	s_waitcnt lgkmcnt(0)
	s_load_dword s3, s[0:1], 0x120
	s_add_u32 s4, s0, 0x120
	s_addc_u32 s5, s1, 0
	s_waitcnt lgkmcnt(0)
	s_load_dwordx4 s[28:31], s[0:1], 0x110
	v_readlane_b32 s8, v244, 1
	v_readlane_b32 s9, v244, 2
	s_waitcnt lgkmcnt(0)
	s_cmp_lt_i32 s29, 6
	s_cselect_b64 s[6:7], -1, 0
	s_xor_b64 s[8:9], s[8:9], -1
	s_or_b64 s[6:7], s[6:7], s[8:9]
	s_and_b64 vcc, exec, s[6:7]
	s_cbranch_vccnz .LBB0_703
	s_waitcnt vmcnt(0)
	s_waitcnt vmcnt(63) expcnt(7) lgkmcnt(15)
	s_barrier
	s_and_saveexec_b64 s[6:7], s[56:57]
	s_cbranch_execz .LBB0_702
	v_readlane_b32 s8, v244, 0
	s_waitcnt vmcnt(0) expcnt(0) lgkmcnt(0)
	s_nop 0
	v_mov_b32_e32 v0, s8
	ds_read_b32 v2, v0
	ds_read_b32 v0, v0 offset:4
	s_waitcnt lgkmcnt(1)
	v_cmp_ne_u32_e32 vcc, 0, v2
	s_cbranch_vccnz .LBB0_673
	s_load_dwordx2 s[10:11], s[4:5], 0x4
	s_add_u32 s4, s58, 0x1000
	s_addc_u32 s5, s59, 0
	s_add_u32 s8, s58, 0x1100
	s_addc_u32 s9, s59, 0
	s_waitcnt lgkmcnt(0)
	s_mul_i32 s3, s10, s3
	s_add_u32 s10, s58, 0x1200
	s_mul_i32 s3, s3, s11
	s_addc_u32 s11, s59, 0
	s_add_u32 s12, s58, 0x1300
	s_addc_u32 s13, s59, 0
	s_mov_b32 s20, 1
	v_mov_b32_e32 v16, 0
	s_branch .LBB0_663

.Ltc_done:
	s_cmp_lt_u32 s2, 0x80
	s_cbranch_scc1 .Lvob_done
	v_lshrrev_b32_e32 v0, 6, v204
	v_and_b32_e32 v1, 63, v204
	v_lshlrev_b32_e32 v2, 4, v1
	v_lshlrev_b32_e32 v3, 5, v1
	v_readfirstlane_b32 s4, v0
	s_sub_u32 s5, s2, 0x80
	s_lshl_b32 s5, s5, 2
	s_add_u32 s4, s4, s5
	s_add_u32 s4, s4, 0x1100
	s_cmpk_ge_u32 s4, 0x2200
	s_cbranch_scc1 .Lvob_done
	s_mul_i32 s6, s4, 0x5400
	s_add_u32 s6, s6, 0x8009000
	s_add_u32 s10, s94, s6
	s_addc_u32 s11, s95, 0
	s_lshl_b32 s6, s4, 12
	s_add_u32 s7, s6, 0x6a00000
	s_add_u32 s6, s6, 0x6400000
	s_cmpk_lt_u32 s4, 0x2000
	s_cselect_b32 s6, s6, s7
	s_add_u32 s14, s92, s6
	s_addc_u32 s15, s93, 0
	global_load_dwordx4 v[8:11], v2, s[10:11]
	global_load_dwordx4 v[12:15], v2, s[10:11] offset:1024
.Lvob_loop:
	s_add_u32 s12, s4, 1536
	s_cmpk_lt_u32 s12, 0x2200
	s_cselect_b32 s13, s12, s4
	s_mul_i32 s6, s13, 0x5400
	s_add_u32 s6, s6, 0x8009000
	s_add_u32 s10, s94, s6
	s_addc_u32 s11, s95, 0
	s_lshl_b32 s6, s13, 12
	s_add_u32 s7, s6, 0x6a00000
	s_add_u32 s6, s6, 0x6400000
	s_cmpk_lt_u32 s13, 0x2000
	s_cselect_b32 s6, s6, s7
	s_add_u32 s16, s92, s6
	s_addc_u32 s17, s93, 0
	global_load_dwordx4 v[16:19], v2, s[10:11]
	global_load_dwordx4 v[20:23], v2, s[10:11] offset:1024
	s_waitcnt vmcnt(2)
	v_lshlrev_b32_e32 v24, 16, v8
	v_and_b32_e32 v25, 0xffff0000, v8
	v_lshlrev_b32_e32 v26, 16, v9
	v_and_b32_e32 v27, 0xffff0000, v9
	v_lshlrev_b32_e32 v28, 16, v10
	v_and_b32_e32 v29, 0xffff0000, v10
	v_lshlrev_b32_e32 v30, 16, v11
	v_and_b32_e32 v31, 0xffff0000, v11
	v_lshlrev_b32_e32 v32, 16, v12
	v_and_b32_e32 v33, 0xffff0000, v12
	v_lshlrev_b32_e32 v34, 16, v13
	v_and_b32_e32 v35, 0xffff0000, v13
	v_lshlrev_b32_e32 v36, 16, v14
	v_and_b32_e32 v37, 0xffff0000, v14
	v_lshlrev_b32_e32 v38, 16, v15
	v_and_b32_e32 v39, 0xffff0000, v15
	global_store_dwordx4 v3, v[24:27], s[14:15]
	global_store_dwordx4 v3, v[28:31], s[14:15] offset:16
	global_store_dwordx4 v3, v[32:35], s[14:15] offset:2048
	global_store_dwordx4 v3, v[36:39], s[14:15] offset:2064
	s_mov_b32 s4, s12
	s_cmpk_lt_u32 s4, 0x2200
	s_cbranch_scc0 .Lvob_drain
	s_add_u32 s12, s4, 1536
	s_cmpk_lt_u32 s12, 0x2200
	s_cselect_b32 s13, s12, s4
	s_mul_i32 s6, s13, 0x5400
	s_add_u32 s6, s6, 0x8009000
	s_add_u32 s10, s94, s6
	s_addc_u32 s11, s95, 0
	s_lshl_b32 s6, s13, 12
	s_add_u32 s7, s6, 0x6a00000
	s_add_u32 s6, s6, 0x6400000
	s_cmpk_lt_u32 s13, 0x2000
	s_cselect_b32 s6, s6, s7
	s_add_u32 s14, s92, s6
	s_addc_u32 s15, s93, 0
	global_load_dwordx4 v[8:11], v2, s[10:11]
	global_load_dwordx4 v[12:15], v2, s[10:11] offset:1024
	s_waitcnt vmcnt(2)
	v_lshlrev_b32_e32 v40, 16, v16
	v_and_b32_e32 v41, 0xffff0000, v16
	v_lshlrev_b32_e32 v42, 16, v17
	v_and_b32_e32 v43, 0xffff0000, v17
	v_lshlrev_b32_e32 v44, 16, v18
	v_and_b32_e32 v45, 0xffff0000, v18
	v_lshlrev_b32_e32 v46, 16, v19
	v_and_b32_e32 v47, 0xffff0000, v19
	v_lshlrev_b32_e32 v48, 16, v20
	v_and_b32_e32 v49, 0xffff0000, v20
	v_lshlrev_b32_e32 v50, 16, v21
	v_and_b32_e32 v51, 0xffff0000, v21
	v_lshlrev_b32_e32 v52, 16, v22
	v_and_b32_e32 v53, 0xffff0000, v22
	v_lshlrev_b32_e32 v54, 16, v23
	v_and_b32_e32 v55, 0xffff0000, v23
	global_store_dwordx4 v3, v[40:43], s[16:17]
	global_store_dwordx4 v3, v[44:47], s[16:17] offset:16
	global_store_dwordx4 v3, v[48:51], s[16:17] offset:2048
	global_store_dwordx4 v3, v[52:55], s[16:17] offset:2064
	s_mov_b32 s4, s12
	s_cmpk_lt_u32 s4, 0x2200
	s_cbranch_scc0 .Lvob_drain
	s_branch .Lvob_loop

.Lvob_done:
	s_load_dword s3, s[0:1], 0x120
	s_add_u32 s4, s0, 0x120
	s_addc_u32 s5, s1, 0
	s_waitcnt lgkmcnt(0)
	s_load_dword s3, s[0:1], 0x120
	s_add_u32 s4, s0, 0x120
	s_addc_u32 s5, s1, 0
	s_waitcnt lgkmcnt(0)
	s_load_dwordx4 s[28:31], s[0:1], 0x110
	v_readlane_b32 s8, v244, 1
	v_readlane_b32 s9, v244, 2
	s_waitcnt lgkmcnt(0)
	s_cmp_lt_i32 s29, 7
	s_cselect_b64 s[6:7], -1, 0
	s_xor_b64 s[8:9], s[8:9], -1
	s_or_b64 s[6:7], s[6:7], s[8:9]
	s_and_b64 vcc, exec, s[6:7]
	s_cbranch_vccnz .LBB0_783
	s_waitcnt vmcnt(0)
	s_waitcnt vmcnt(63) expcnt(7) lgkmcnt(15)
	s_barrier
	s_and_saveexec_b64 s[6:7], s[56:57]
	s_cbranch_execz .LBB0_782
	v_readlane_b32 s8, v244, 0
	s_waitcnt vmcnt(0) expcnt(0) lgkmcnt(0)
	s_nop 0
	v_mov_b32_e32 v0, s8
	ds_read_b32 v2, v0
	ds_read_b32 v0, v0 offset:4
	s_waitcnt lgkmcnt(1)
	v_cmp_ne_u32_e32 vcc, 0, v2
	s_cbranch_vccnz .LBB0_753
	v_readlane_b32 s4, v244, 4
	v_readlane_b32 s5, v244, 5
	s_load_dwordx2 s[10:11], s[4:5], 0x4
	s_load_dword s3, s[0:1], 0x120
	s_add_u32 s4, s58, 0x1000
	s_addc_u32 s5, s59, 0
	s_add_u32 s8, s58, 0x1100
	s_addc_u32 s9, s59, 0
	s_waitcnt lgkmcnt(0)
	s_mul_i32 s3, s10, s3
	s_add_u32 s10, s58, 0x1200
	s_mul_i32 s3, s3, s11
	s_addc_u32 s11, s59, 0
	s_add_u32 s12, s58, 0x1300
	s_addc_u32 s13, s59, 0
	s_mov_b32 s20, 1
	v_mov_b32_e32 v16, 0
	s_branch .LBB0_743
